# v47 + P5 epilogue operands (256 shift cols, 256 gate bounds, 256 rstd) staged to spare LDS by LDS-DMA in the last K-iteration; epilogue head uses ds_read instead of global loads + vmcnt(0)
# speedup vs baseline: 1.0167x; 1.0126x over previous
.LBB0_1375:
	ds_read_b128 v[10:13], v225
	ds_read_b128 v[14:17], v225 offset:1024
	ds_read_b128 v[26:29], v225 offset:2048
	ds_read_b128 v[30:33], v225 offset:3072
	s_add_u32 s18, s34, 0xfffc0080
	s_addc_u32 s19, s35, -1
	s_cmp_eq_u32 vcc_lo, 12
	s_cselect_b32 s19, s3, s19
	s_cselect_b32 s18, s5, s18
	s_cselect_b32 s55, s39, s57
	s_cselect_b32 s54, s41, s56
	s_cbranch_scc0 .Lp5_nopf
	s_min_i32 s20, s4, 0x80
	s_ashr_i32 s20, s20, 3
	s_mul_hi_i32 s21, s20, 0x6000
	s_mulk_i32 s20, 0x6000
	s_add_u32 s20, s77, s20
	s_addc_u32 s21, s78, s21
	s_lshl_b32 s32, s2, 10
	s_add_u32 s20, s20, s32
	s_addc_u32 s21, s21, 0
	v_and_b32_e32 v229, 63, v170
	v_lshlrev_b32_e32 v229, 4, v229
	s_mov_b32 m0, 0x20000
	s_nop 0
	global_load_lds_dwordx4 v229, s[20:21]
	s_add_u32 s20, s6, s32
	s_addc_u32 s21, s7, 0
	s_add_u32 s20, s20, 0xfffff800
	s_addc_u32 s21, s21, -1
	s_mov_b32 m0, 0x20400
	s_nop 0
	global_load_lds_dwordx4 v229, s[20:21]
	s_lshl_b32 s32, s4, 10
	s_add_u32 s20, s0, s32
	s_addc_u32 s21, s1, 0
	s_mov_b32 m0, 0x20800
	s_nop 0
	global_load_lds_dwordx4 v229, s[20:21]
.Lp5_nopf:
	v_lshl_add_u64 v[202:203], s[34:35], 0, v[178:179]
	s_add_i32 m0, s72, 0xc000
	ds_read_b128 v[34:37], v226
	ds_read_b128 v[38:41], v226 offset:1024
	ds_read_b128 v[50:53], v226 offset:2048
	ds_read_b128 v[54:57], v226 offset:3072
	ds_read_b128 v[186:189], v226 offset:4096
	ds_read_b128 v[190:193], v226 offset:5120
	ds_read_b128 v[194:197], v226 offset:6144
	ds_read_b128 v[198:201], v226 offset:7168
	global_load_lds_dwordx4 v[202:203], off
	v_lshl_add_u64 v[202:203], s[34:35], 0, v[180:181]
	s_add_i32 m0, s72, 0xe000
	s_nop 0
	global_load_lds_dwordx4 v[202:203], off
	ds_read_b128 v[202:205], v227
	ds_read_b128 v[206:209], v227 offset:1024
	ds_read_b128 v[210:213], v227 offset:2048
	ds_read_b128 v[214:217], v227 offset:3072
	s_waitcnt lgkmcnt(0)
	s_setprio 1
	s_barrier
	v_mfma_f32_16x16x32_bf16 v[158:161], v[10:13], v[34:37], v[158:161]
	v_mfma_f32_16x16x32_bf16 v[154:157], v[26:29], v[34:37], v[154:157]
	v_mfma_f32_16x16x32_bf16 v[142:145], v[10:13], v[50:53], v[142:145]
	v_mfma_f32_16x16x32_bf16 v[138:141], v[26:29], v[50:53], v[138:141]
	v_mfma_f32_16x16x32_bf16 v[126:129], v[10:13], v[186:189], v[126:129]
	v_mfma_f32_16x16x32_bf16 v[122:125], v[26:29], v[186:189], v[122:125]
	v_mfma_f32_16x16x32_bf16 v[110:113], v[10:13], v[194:197], v[110:113]
	v_mfma_f32_16x16x32_bf16 v[106:109], v[26:29], v[194:197], v[106:109]
	v_mfma_f32_16x16x32_bf16 v[158:161], v[14:17], v[38:41], v[158:161]
	v_mfma_f32_16x16x32_bf16 v[154:157], v[30:33], v[38:41], v[154:157]
	v_mfma_f32_16x16x32_bf16 v[142:145], v[14:17], v[54:57], v[142:145]
	v_mfma_f32_16x16x32_bf16 v[138:141], v[30:33], v[54:57], v[138:141]
	v_mfma_f32_16x16x32_bf16 v[126:129], v[14:17], v[190:193], v[126:129]
	v_mfma_f32_16x16x32_bf16 v[122:125], v[30:33], v[190:193], v[122:125]
	v_mfma_f32_16x16x32_bf16 v[110:113], v[14:17], v[198:201], v[110:113]
	v_mfma_f32_16x16x32_bf16 v[106:109], v[30:33], v[198:201], v[106:109]
	v_mfma_f32_16x16x32_bf16 v[150:153], v[202:205], v[34:37], v[150:153]
	v_mfma_f32_16x16x32_bf16 v[34:37], v[210:213], v[34:37], v[146:149]
	v_mfma_f32_16x16x32_bf16 v[150:153], v[206:209], v[38:41], v[150:153]
	v_mfma_f32_16x16x32_bf16 v[34:37], v[214:217], v[38:41], v[34:37]
	v_mfma_f32_16x16x32_bf16 v[38:41], v[202:205], v[50:53], v[134:137]
	v_mfma_f32_16x16x32_bf16 v[50:53], v[210:213], v[50:53], v[130:133]
	v_mfma_f32_16x16x32_bf16 v[114:117], v[210:213], v[186:189], v[114:117]
	v_mfma_f32_16x16x32_bf16 v[102:105], v[202:205], v[194:197], v[102:105]
	v_mfma_f32_16x16x32_bf16 v[98:101], v[210:213], v[194:197], v[98:101]
	v_mfma_f32_16x16x32_bf16 v[38:41], v[206:209], v[54:57], v[38:41]
	v_mfma_f32_16x16x32_bf16 v[50:53], v[214:217], v[54:57], v[50:53]
	v_mfma_f32_16x16x32_bf16 v[54:57], v[202:205], v[186:189], v[118:121]
	v_mfma_f32_16x16x32_bf16 v[114:117], v[214:217], v[190:193], v[114:117]
	v_mfma_f32_16x16x32_bf16 v[102:105], v[206:209], v[198:201], v[102:105]
	v_mfma_f32_16x16x32_bf16 v[98:101], v[214:217], v[198:201], v[98:101]
	v_mfma_f32_16x16x32_bf16 v[54:57], v[206:209], v[190:193], v[54:57]
	s_barrier
	s_setprio 0
	s_add_i32 s20, s33, s71
	v_lshl_add_u64 v[222:223], s[54:55], 0, v[164:165]
	s_mov_b32 m0, s20
	s_nop 0
	global_load_lds_dwordx4 v[222:223], off
	v_lshl_add_u64 v[238:239], s[54:55], 0, v[168:169]
	s_add_i32 m0, s20, 0x2000
	s_nop 0
	global_load_lds_dwordx4 v[238:239], off
	s_mov_b32 m0, s72
	v_lshl_add_u64 v[240:241], s[18:19], 0, v[162:163]
	ds_read_b128 v[118:121], v226 offset:16384
	ds_read_b128 v[130:133], v226 offset:17408
	ds_read_b128 v[134:137], v226 offset:18432
	ds_read_b128 v[146:149], v226 offset:19456
	ds_read_b128 v[186:189], v226 offset:20480
	ds_read_b128 v[190:193], v226 offset:21504
	ds_read_b128 v[194:197], v226 offset:22528
	ds_read_b128 v[198:201], v226 offset:23552
	global_load_lds_dwordx4 v[240:241], off
	v_lshl_add_u64 v[242:243], s[18:19], 0, v[166:167]
	s_mov_b32 m0, s73
	s_nop 0
	global_load_lds_dwordx4 v[242:243], off
	s_cmp_eq_u32 vcc_lo, 12
	s_cbranch_scc1 .Lp5_q2last
	s_waitcnt vmcnt(6)
	s_branch .Lp5_q2join

.Lp5_q2join:
	s_waitcnt lgkmcnt(0)
	s_setprio 1
	s_barrier
	v_mfma_f32_16x16x32_bf16 v[94:97], v[10:13], v[118:121], v[94:97]
	v_mfma_f32_16x16x32_bf16 v[90:93], v[26:29], v[118:121], v[90:93]
	v_mfma_f32_16x16x32_bf16 v[78:81], v[10:13], v[134:137], v[78:81]
	v_mfma_f32_16x16x32_bf16 v[74:77], v[26:29], v[134:137], v[74:77]
	v_mfma_f32_16x16x32_bf16 v[62:65], v[10:13], v[186:189], v[62:65]
	v_mfma_f32_16x16x32_bf16 v[58:61], v[26:29], v[186:189], v[58:61]
	v_mfma_f32_16x16x32_bf16 v[10:13], v[10:13], v[194:197], v[22:25]
	v_mfma_f32_16x16x32_bf16 v[94:97], v[14:17], v[130:133], v[94:97]
	v_mfma_f32_16x16x32_bf16 v[90:93], v[30:33], v[130:133], v[90:93]
	v_mfma_f32_16x16x32_bf16 v[78:81], v[14:17], v[146:149], v[78:81]
	v_mfma_f32_16x16x32_bf16 v[74:77], v[30:33], v[146:149], v[74:77]
	v_mfma_f32_16x16x32_bf16 v[62:65], v[14:17], v[190:193], v[62:65]
	v_mfma_f32_16x16x32_bf16 v[58:61], v[30:33], v[190:193], v[58:61]
	v_mfma_f32_16x16x32_bf16 v[10:13], v[14:17], v[198:201], v[10:13]
	v_mfma_f32_16x16x32_bf16 v[14:17], v[26:29], v[194:197], v[18:21]
	v_mfma_f32_16x16x32_bf16 v[14:17], v[30:33], v[198:201], v[14:17]
	v_mfma_f32_16x16x32_bf16 v[18:21], v[202:205], v[118:121], v[86:89]
	v_mfma_f32_16x16x32_bf16 v[26:29], v[206:209], v[130:133], v[18:21]
	v_mfma_f32_16x16x32_bf16 v[18:21], v[210:213], v[118:121], v[82:85]
	v_mfma_f32_16x16x32_bf16 v[30:33], v[214:217], v[130:133], v[18:21]
	v_mfma_f32_16x16x32_bf16 v[18:21], v[202:205], v[134:137], v[70:73]
	v_mfma_f32_16x16x32_bf16 v[70:73], v[206:209], v[146:149], v[18:21]
	v_mfma_f32_16x16x32_bf16 v[18:21], v[210:213], v[134:137], v[66:69]
	v_mfma_f32_16x16x32_bf16 v[66:69], v[214:217], v[146:149], v[18:21]
	v_mfma_f32_16x16x32_bf16 v[18:21], v[202:205], v[186:189], v[46:49]
	v_mfma_f32_16x16x32_bf16 v[46:49], v[206:209], v[190:193], v[18:21]
	v_mfma_f32_16x16x32_bf16 v[18:21], v[210:213], v[186:189], v[42:45]
	v_mfma_f32_16x16x32_bf16 v[6:9], v[202:205], v[194:197], v[6:9]
	v_mfma_f32_16x16x32_bf16 v[2:5], v[210:213], v[194:197], v[2:5]
	v_mfma_f32_16x16x32_bf16 v[42:45], v[214:217], v[190:193], v[18:21]
	v_mfma_f32_16x16x32_bf16 v[6:9], v[206:209], v[198:201], v[6:9]
	v_mfma_f32_16x16x32_bf16 v[2:5], v[214:217], v[198:201], v[2:5]
	s_barrier
	s_setprio 0
	s_add_u32 s20, s54, 0x40000
	s_addc_u32 s21, s55, 0
	s_add_i32 s60, s64, s71
	v_lshl_add_u64 v[246:247], s[20:21], 0, v[164:165]
	s_mov_b32 m0, s60
	s_nop 0
	global_load_lds_dwordx4 v[246:247], off
	v_lshl_add_u64 v[246:247], s[20:21], 0, v[168:169]
	s_add_i32 m0, s60, 0x2000
	s_nop 0
	global_load_lds_dwordx4 v[246:247], off
	s_add_i32 s20, 0, 0x18000
	v_add_u32_e32 v86, s20, v175
	ds_read_b128 v[18:21], v86
	ds_read_b128 v[22:25], v86 offset:1024
	ds_read_b128 v[82:85], v86 offset:2048
	ds_read_b128 v[86:89], v86 offset:3072
	s_add_u32 s18, s18, 0x40000
	s_addc_u32 s19, s19, 0
	s_mov_b32 m0, s74
	v_lshl_add_u64 v[134:135], s[18:19], 0, v[162:163]
	ds_read_b128 v[118:121], v226 offset:32768
	ds_read_b128 v[130:133], v226 offset:33792
	ds_read_b128 v[186:189], v226 offset:34816
	ds_read_b128 v[190:193], v226 offset:35840
	ds_read_b128 v[194:197], v226 offset:36864
	ds_read_b128 v[198:201], v226 offset:37888
	ds_read_b128 v[202:205], v226 offset:38912
	ds_read_b128 v[206:209], v226 offset:39936
	global_load_lds_dwordx4 v[134:135], off
	v_lshl_add_u64 v[134:135], s[18:19], 0, v[166:167]
	s_mov_b32 m0, s75
	s_nop 0
	global_load_lds_dwordx4 v[134:135], off
	s_add_i32 s21, 0, 0x1c000
	v_add_u32_e32 v244, s21, v175
	ds_read_b128 v[210:213], v244
	ds_read_b128 v[214:217], v244 offset:1024
	ds_read_b128 v[218:221], v244 offset:2048
	ds_read_b128 v[234:237], v244 offset:3072
	s_waitcnt vmcnt(8)
	s_waitcnt lgkmcnt(0)
	s_setprio 1
	s_barrier
	v_mfma_f32_16x16x32_bf16 v[134:137], v[18:21], v[118:121], v[158:161]
	v_mfma_f32_16x16x32_bf16 v[158:161], v[22:25], v[130:133], v[134:137]
	v_mfma_f32_16x16x32_bf16 v[134:137], v[82:85], v[118:121], v[154:157]
	v_mfma_f32_16x16x32_bf16 v[154:157], v[86:89], v[130:133], v[134:137]
	v_mfma_f32_16x16x32_bf16 v[134:137], v[18:21], v[186:189], v[142:145]
	v_mfma_f32_16x16x32_bf16 v[142:145], v[22:25], v[190:193], v[134:137]
	v_mfma_f32_16x16x32_bf16 v[134:137], v[82:85], v[186:189], v[138:141]
	v_mfma_f32_16x16x32_bf16 v[126:129], v[18:21], v[194:197], v[126:129]
	v_mfma_f32_16x16x32_bf16 v[122:125], v[82:85], v[194:197], v[122:125]
	v_mfma_f32_16x16x32_bf16 v[110:113], v[18:21], v[202:205], v[110:113]
	v_mfma_f32_16x16x32_bf16 v[106:109], v[82:85], v[202:205], v[106:109]
	v_mfma_f32_16x16x32_bf16 v[138:141], v[86:89], v[190:193], v[134:137]
	v_mfma_f32_16x16x32_bf16 v[126:129], v[22:25], v[198:201], v[126:129]
	v_mfma_f32_16x16x32_bf16 v[122:125], v[86:89], v[198:201], v[122:125]
	v_mfma_f32_16x16x32_bf16 v[110:113], v[22:25], v[206:209], v[110:113]
	v_mfma_f32_16x16x32_bf16 v[106:109], v[86:89], v[206:209], v[106:109]
	v_mfma_f32_16x16x32_bf16 v[34:37], v[218:221], v[118:121], v[34:37]
	v_mfma_f32_16x16x32_bf16 v[134:137], v[210:213], v[118:121], v[150:153]
	v_mfma_f32_16x16x32_bf16 v[146:149], v[234:237], v[130:133], v[34:37]
	v_mfma_f32_16x16x32_bf16 v[34:37], v[210:213], v[186:189], v[38:41]
	v_mfma_f32_16x16x32_bf16 v[150:153], v[214:217], v[130:133], v[134:137]
	v_mfma_f32_16x16x32_bf16 v[134:137], v[214:217], v[190:193], v[34:37]
	v_mfma_f32_16x16x32_bf16 v[34:37], v[218:221], v[186:189], v[50:53]
	v_mfma_f32_16x16x32_bf16 v[130:133], v[234:237], v[190:193], v[34:37]
	v_mfma_f32_16x16x32_bf16 v[34:37], v[210:213], v[194:197], v[54:57]
	v_mfma_f32_16x16x32_bf16 v[118:121], v[214:217], v[198:201], v[34:37]
	v_mfma_f32_16x16x32_bf16 v[34:37], v[218:221], v[194:197], v[114:117]
	v_mfma_f32_16x16x32_bf16 v[114:117], v[234:237], v[198:201], v[34:37]
	v_mfma_f32_16x16x32_bf16 v[34:37], v[210:213], v[202:205], v[102:105]
	v_mfma_f32_16x16x32_bf16 v[102:105], v[214:217], v[206:209], v[34:37]
	v_mfma_f32_16x16x32_bf16 v[34:37], v[218:221], v[202:205], v[98:101]
	v_mfma_f32_16x16x32_bf16 v[98:101], v[234:237], v[206:209], v[34:37]
	s_barrier
	s_setprio 0
	s_add_i32 s18, s20, s71
	v_lshl_add_u64 v[248:249], v[222:223], 0, s[24:25]
	s_mov_b32 m0, s18
	s_nop 0
	global_load_lds_dwordx4 v[248:249], off
	v_lshl_add_u64 v[248:249], v[238:239], 0, s[24:25]
	s_add_i32 m0, s18, 0x2000
	s_nop 0
	global_load_lds_dwordx4 v[248:249], off
	s_mov_b32 m0, s95
	v_lshl_add_u64 v[202:203], v[240:241], 0, s[24:25]
	s_nop 2
	ds_read_b128 v[34:37], v226 offset:49152
	ds_read_b128 v[38:41], v226 offset:50176
	ds_read_b128 v[50:53], v226 offset:51200
	ds_read_b128 v[54:57], v226 offset:52224
	ds_read_b128 v[186:189], v226 offset:53248
	ds_read_b128 v[190:193], v226 offset:54272
	ds_read_b128 v[194:197], v226 offset:55296
	ds_read_b128 v[198:201], v226 offset:56320
	global_load_lds_dwordx4 v[202:203], off
	v_lshl_add_u64 v[202:203], v[242:243], 0, s[24:25]
	s_mov_b32 m0, s96
	s_nop 0
	global_load_lds_dwordx4 v[202:203], off
	s_add_u32 s18, s54, 0x40080
	s_addc_u32 s19, s55, 0
	s_add_i32 s20, s21, s71
	v_lshl_add_u64 v[250:251], s[18:19], 0, v[164:165]
	s_mov_b32 m0, s20
	s_nop 0
	global_load_lds_dwordx4 v[250:251], off
	v_lshl_add_u64 v[250:251], s[18:19], 0, v[168:169]
	s_add_i32 m0, s20, 0x2000
	s_nop 0
	global_load_lds_dwordx4 v[250:251], off
	s_waitcnt vmcnt(6)
	s_waitcnt lgkmcnt(0)
	s_setprio 1
	s_barrier
	v_mfma_f32_16x16x32_bf16 v[94:97], v[18:21], v[34:37], v[94:97]
	v_mfma_f32_16x16x32_bf16 v[78:81], v[18:21], v[50:53], v[78:81]
	v_mfma_f32_16x16x32_bf16 v[62:65], v[18:21], v[186:189], v[62:65]
	v_mfma_f32_16x16x32_bf16 v[10:13], v[18:21], v[194:197], v[10:13]
	v_mfma_f32_16x16x32_bf16 v[94:97], v[22:25], v[38:41], v[94:97]
	v_mfma_f32_16x16x32_bf16 v[90:93], v[82:85], v[34:37], v[90:93]
	v_mfma_f32_16x16x32_bf16 v[78:81], v[22:25], v[54:57], v[78:81]
	v_mfma_f32_16x16x32_bf16 v[74:77], v[82:85], v[50:53], v[74:77]
	v_mfma_f32_16x16x32_bf16 v[62:65], v[22:25], v[190:193], v[62:65]
	v_mfma_f32_16x16x32_bf16 v[58:61], v[82:85], v[186:189], v[58:61]
	v_mfma_f32_16x16x32_bf16 v[22:25], v[22:25], v[198:201], v[10:13]
	v_mfma_f32_16x16x32_bf16 v[10:13], v[82:85], v[194:197], v[14:17]
	v_mfma_f32_16x16x32_bf16 v[90:93], v[86:89], v[38:41], v[90:93]
	v_mfma_f32_16x16x32_bf16 v[74:77], v[86:89], v[54:57], v[74:77]
	v_mfma_f32_16x16x32_bf16 v[58:61], v[86:89], v[190:193], v[58:61]
	v_mfma_f32_16x16x32_bf16 v[18:21], v[86:89], v[198:201], v[10:13]
	v_mfma_f32_16x16x32_bf16 v[10:13], v[210:213], v[34:37], v[26:29]
	v_mfma_f32_16x16x32_bf16 v[86:89], v[214:217], v[38:41], v[10:13]
	v_mfma_f32_16x16x32_bf16 v[10:13], v[218:221], v[34:37], v[30:33]
	v_mfma_f32_16x16x32_bf16 v[82:85], v[234:237], v[38:41], v[10:13]
	v_mfma_f32_16x16x32_bf16 v[10:13], v[210:213], v[50:53], v[70:73]
	v_mfma_f32_16x16x32_bf16 v[70:73], v[214:217], v[54:57], v[10:13]
	v_mfma_f32_16x16x32_bf16 v[10:13], v[218:221], v[50:53], v[66:69]
	v_mfma_f32_16x16x32_bf16 v[66:69], v[234:237], v[54:57], v[10:13]
	v_mfma_f32_16x16x32_bf16 v[10:13], v[210:213], v[186:189], v[46:49]
	v_mfma_f32_16x16x32_bf16 v[46:49], v[214:217], v[190:193], v[10:13]
	v_mfma_f32_16x16x32_bf16 v[10:13], v[218:221], v[186:189], v[42:45]
	v_mfma_f32_16x16x32_bf16 v[6:9], v[210:213], v[194:197], v[6:9]
	v_mfma_f32_16x16x32_bf16 v[2:5], v[218:221], v[194:197], v[2:5]
	v_mfma_f32_16x16x32_bf16 v[42:45], v[234:237], v[190:193], v[10:13]
	v_mfma_f32_16x16x32_bf16 v[6:9], v[214:217], v[198:201], v[6:9]
	v_mfma_f32_16x16x32_bf16 v[2:5], v[234:237], v[198:201], v[2:5]
	s_add_i32 vcc_lo, vcc_lo, 2
	s_add_u32 s34, s34, 0x100
	s_addc_u32 s35, s35, 0
	s_add_u32 s56, s56, 0x100
	s_addc_u32 s57, s57, 0
	s_cmp_gt_u32 vcc_lo, 13
	s_cbranch_scc0 .Ldfr_p5_r
	s_cmpk_gt_u32 s63, 0xff
	s_cbranch_scc1 .Ldfr_p5_b
	s_barrier
.Ldfr_p5_b:
	s_mov_b32 s20, 0xbfb8aa3b
	s_setprio 0
	s_min_i32 s3, s4, 0x80
	s_ashr_i32 s5, s3, 3
	s_lshl_b32 s3, s2, 8
	s_mul_hi_i32 s19, s5, 0x6000
	s_mulk_i32 s5, 0x6000
	v_or_b32_e32 v186, s3, v224
	s_add_u32 s18, s77, s5
	s_addc_u32 s19, s78, s19
	v_ashrrev_i32_e32 v187, 31, v186
	v_lshlrev_b32_e32 v14, 2, v224
	v_add_u32_e32 v14, 0x20000, v14
	ds_read_b128 v[50:53], v14 offset:16
	ds_read_b128 v[54:57], v14
	ds_read_b128 v[26:29], v14 offset:528
	ds_read_b128 v[30:33], v14 offset:512
	s_add_i32 s5, s2, -2
	s_cmp_gt_u32 s5, 3
	s_cbranch_scc1 .LBB0_1378
	ds_read_b128 v[38:41], v14 offset:1024
	ds_read_b128 v[34:37], v14 offset:1040
	ds_read_b128 v[10:13], v14 offset:1536
	ds_read_b128 v[14:17], v14 offset:1552
.LBB0_1378:
	s_lshl_b32 s41, s4, 8
	s_add_i32 s41, s41, s94
	v_or_b32_e32 v204, s41, v171
	v_or_b32_e32 v214, 16, v204
	v_or_b32_e32 v210, 32, v204
	v_or_b32_e32 v206, 48, v204
	v_add_u32_e32 v198, 0x90, v204
	v_ashrrev_i32_e32 v205, 31, v204
	v_ashrrev_i32_e32 v215, 31, v214
	v_ashrrev_i32_e32 v211, 31, v210
	v_ashrrev_i32_e32 v207, 31, v206
	v_ashrrev_i32_e32 v199, 31, v198
	v_add_u32_e32 v194, 0xa0, v204
	v_add_u32_e32 v188, 0xb0, v204
	v_add_u32_e32 v192, s94, v171
	v_lshlrev_b32_e32 v192, 2, v192
	v_add_u32_e32 v192, 0x20800, v192
	v_ashrrev_i32_e32 v195, 31, v194
	v_ashrrev_i32_e32 v189, 31, v188
	ds_read_b32 v218, v192
	ds_read_b32 v216, v192 offset:64
	ds_read_b32 v212, v192 offset:128
	ds_read_b32 v208, v192 offset:192
	ds_read_b32 v200, v192 offset:576
	ds_read_b32 v196, v192 offset:640
	ds_read_b32 v190, v192 offset:704
	ds_read_b32 v202, v192 offset:512
	s_ashr_i32 s39, s2, 1
	s_cmpk_gt_u32 s3, 0x1ff
	v_add_u32_e32 v176, 0xfffff600, v186
	s_cselect_b64 s[2:3], -1, 0
	s_cmp_gt_i32 s39, 2
	v_ashrrev_i32_e32 v192, 3, v176
	s_cselect_b64 s[34:35], -1, 0
	s_cmp_gt_u32 s39, 7
	v_ashrrev_i32_e32 v193, 31, v192
	s_cselect_b64 s[56:57], -1, 0
	s_cmp_eq_u32 s39, 1
	v_and_b32_e32 v191, 0x178, v186
	s_waitcnt lgkmcnt(0)
	v_sub_f32_e32 v242, 1.0, v38
	v_sub_f32_e32 v241, 1.0, v39
	v_sub_f32_e32 v240, 1.0, v40
	v_sub_f32_e32 v239, 1.0, v41
	v_sub_f32_e32 v238, 1.0, v34
	v_sub_f32_e32 v234, 1.0, v35
	v_sub_f32_e32 v233, 1.0, v36
	v_sub_f32_e32 v229, 1.0, v37
	s_mov_b64 s[4:5], -1
	v_lshlrev_b64 v[192:193], 15, v[192:193]
	s_cselect_b64 s[54:55], -1, 0
	s_and_b64 vcc, exec, s[2:3]
	v_pk_fma_f32 v[220:221], v[158:159], v[218:219], v[54:55] op_sel_hi:[1,0,1]
	v_pk_fma_f32 v[160:161], v[160:161], v[218:219], v[56:57] op_sel_hi:[1,0,1]
	v_pk_fma_f32 v[154:155], v[154:155], v[218:219], v[50:51] op_sel_hi:[1,0,1]
	v_pk_fma_f32 v[222:223], v[156:157], v[218:219], v[52:53] op_sel_hi:[1,0,1]
	s_cbranch_vccz .LBB0_1396
	s_and_b64 vcc, exec, s[34:35]
	s_cbranch_vccz .LBB0_1393
	s_cmp_lt_i32 s39, 4
	s_cbranch_scc1 .LBB0_1390
	s_cmp_lg_u32 s39, 4
	s_cbranch_scc0 .LBB0_1387
	s_andn2_b64 vcc, exec, s[56:57]
	s_cbranch_vccnz .LBB0_1384
	v_pk_mul_f32 v[156:157], v[220:221], s[20:21] op_sel_hi:[1,0]
	v_exp_f32_e32 v156, v156
	v_exp_f32_e32 v157, v157
	v_mul_f32_e32 v159, 0xbfb8aa3b, v161
	v_exp_f32_e32 v159, v159
	v_pk_add_f32 v[156:157], v[156:157], 1.0 op_sel_hi:[1,0]
	v_rcp_f32_e32 v156, v156
	v_rcp_f32_e32 v157, v157
	v_mul_f32_e32 v158, 0xbfb8aa3b, v160
	v_mul_f32_e32 v203, 0xbfb8aa3b, v223
	v_max_f32_e32 v176, 0x219392ef, v156
	v_max_f32_e32 v197, 0x219392ef, v157
	v_add_f32_e32 v156, 1.0, v159
	v_mul_f32_e32 v157, 0xbfb8aa3b, v154
	v_mul_f32_e32 v159, 0xbfb8aa3b, v155
	v_rcp_f32_e32 v156, v156
	v_exp_f32_e32 v157, v157
	v_exp_f32_e32 v159, v159
	v_exp_f32_e32 v158, v158
	v_max_f32_e32 v201, 0x219392ef, v156
	v_add_f32_e32 v156, 1.0, v157
	v_add_f32_e32 v157, 1.0, v159
	v_mul_f32_e32 v159, 0xbfb8aa3b, v222
	v_exp_f32_e32 v159, v159
	v_exp_f32_e32 v203, v203
	v_rcp_f32_e32 v156, v156
	v_rcp_f32_e32 v157, v157
	v_pk_add_f32 v[158:159], v[158:159], 1.0 op_sel_hi:[1,0]
	v_add_f32_e32 v203, 1.0, v203
	v_rcp_f32_e32 v158, v158
	v_rcp_f32_e32 v159, v159
	v_rcp_f32_e32 v203, v203
	v_max_f32_e32 v209, 0x219392ef, v156
	v_max_f32_e32 v213, 0x219392ef, v157
	v_lshlrev_b64 v[156:157], 12, v[204:205]
	v_lshl_add_u64 v[156:157], s[16:17], 0, v[156:157]
	v_lshl_add_u64 v[236:237], v[186:187], 1, v[156:157]
	v_max_f32_e32 v158, 0x219392ef, v158
	v_max_f32_e32 v159, 0x219392ef, v159
	v_max_f32_e32 v203, 0x219392ef, v203
	v_add_co_u32_e32 v236, vcc, 0xffffe000, v236
	v_cvt_pk_bf16_f32 v156, v176, v197
	v_cvt_pk_bf16_f32 v157, v158, v201
	v_cvt_pk_bf16_f32 v158, v209, v213
	v_cvt_pk_bf16_f32 v159, v159, v203
	v_addc_co_u32_e32 v237, vcc, -1, v237, vcc
	s_mov_b64 s[4:5], 0
	global_store_dwordx4 v[236:237], v[156:159], off nt
	s_nop 1
	v_lshlrev_b64 v[158:159], 10, v[204:205]
	v_lshl_add_u64 v[156:157], s[8:9], 0, v[158:159]
	s_branch .LBB0_1398
